# FoX tile loop: counted vmcnt so K/V register staging stays two tiles ahead (cumulative-gate load made wave-uniform)
# speedup vs baseline: 1.0053x; 1.0019x over previous
.LBB0_163:
	s_or_b64 exec, exec, s[6:7]
	v_mul_lo_u32 v2, v128, s11
	v_lshlrev_b32_e32 v0, 4, v0
	v_add_u32_e32 v129, v2, v0
	v_mad_u64_u32 v[2:3], s[6:7], v128, 48, v[2:3]
	v_add_u32_e32 v131, v2, v0
	v_lshlrev_b32_e32 v132, 2, v127
	s_waitcnt vmcnt(1)
	ds_write_b128 v129, v[112:115]
	s_waitcnt vmcnt(0)
	ds_write_b128 v131, v[116:119] offset:18432
	s_and_saveexec_b64 s[6:7], s[38:39]
	ds_write_b32 v132, v130 offset:43008
	s_or_b64 exec, exec, s[6:7]
	s_add_u32 s6, s0, -1
	s_addc_u32 s7, s1, -1
	s_and_b64 s[0:1], s[6:7], s[0:1]
	s_cmp_eq_u64 s[0:1], 0
	s_cselect_b64 s[6:7], -1, 0
	s_ff1_i32_b64 s18, s[0:1]
	s_and_b64 vcc, exec, s[6:7]
	s_cbranch_vccnz .LBB0_169
	s_lshl_b32 s48, s18, 6
	v_add_u32_e32 v0, s48, v128
	v_min_i32_e32 v0, 0xfff, v0
	v_mad_i64_i32 v[2:3], s[40:41], v0, s23, v[120:121]
	v_lshlrev_b64 v[2:3], 1, v[2:3]
	v_lshl_add_u64 v[4:5], s[26:27], 0, v[2:3]
	v_lshl_add_u64 v[2:3], s[30:31], 0, v[2:3]
	global_load_dwordx4 v[112:115], v[4:5], off
	global_load_dwordx4 v[116:119], v[2:3], off
	v_and_b32_e32 v2, 63, v127
	v_add_u32_e32 v2, s48, v2
	v_ashrrev_i32_e32 v3, 31, v2
	v_lshl_add_u64 v[2:3], v[2:3], 2, s[42:43]
	global_load_dword v130, v[2:3], off

.LBB0_175:
	s_lshl_b32 s18, s6, 6
	v_add_u32_e32 v0, s18, v128
	v_min_i32_e32 v0, 0xfff, v0
	v_mad_i64_i32 v[2:3], s[0:1], v0, s23, v[120:121]
	v_lshlrev_b64 v[2:3], 1, v[2:3]
	v_lshl_add_u64 v[4:5], s[26:27], 0, v[2:3]
	v_lshl_add_u64 v[2:3], s[30:31], 0, v[2:3]
	global_load_dwordx4 v[6:9], v[4:5], off
	s_nop 0
	global_load_dwordx4 v[2:5], v[2:3], off
	v_and_b32_e32 v10, 63, v127
	v_add_u32_e32 v10, s18, v10
	v_ashrrev_i32_e32 v11, 31, v10
	v_lshl_add_u64 v[10:11], v[10:11], 2, s[42:43]
	global_load_dword v141, v[10:11], off
	s_lshl_b32 s0, s13, 6
	v_cmp_le_i32_e32 vcc, s0, v133
	s_and_saveexec_b64 s[56:57], vcc
	s_cbranch_execz .LBB0_174

.LBB0_183:
	s_and_b64 vcc, exec, s[48:49]
	s_cbranch_vccnz .Lfox_ev_w0
	s_waitcnt vmcnt(3)
	s_branch .Lfox_ev_st

.Lfox_ev_st:
	ds_write_b128 v129, v[112:115] offset:9216
	ds_write_b128 v131, v[116:119] offset:30720
	s_and_saveexec_b64 s[0:1], s[38:39]
	ds_write_b32 v132, v130 offset:43264
	s_or_b64 exec, exec, s[0:1]

.LBB0_191:
	s_lshl_b32 s18, s13, 6
	v_add_u32_e32 v0, s18, v128
	v_min_i32_e32 v0, 0xfff, v0
	v_mad_i64_i32 v[10:11], s[0:1], v0, s23, v[120:121]
	v_lshlrev_b64 v[10:11], 1, v[10:11]
	v_lshl_add_u64 v[12:13], s[26:27], 0, v[10:11]
	v_lshl_add_u64 v[10:11], s[30:31], 0, v[10:11]
	global_load_dwordx4 v[112:115], v[12:13], off
	global_load_dwordx4 v[116:119], v[10:11], off
	v_and_b32_e32 v10, 63, v127
	v_add_u32_e32 v10, s18, v10
	v_ashrrev_i32_e32 v11, 31, v10
	v_lshl_add_u64 v[10:11], v[10:11], 2, s[42:43]
	global_load_dword v130, v[10:11], off
	s_lshl_b32 s0, s7, 6
	v_cmp_le_i32_e32 vcc, s0, v133
	s_and_saveexec_b64 s[58:59], vcc
	s_cbranch_execz .LBB0_189

.LBB0_199:
	s_and_b64 vcc, exec, s[56:57]
	s_cbranch_vccnz .Lfox_od_w0
	s_waitcnt vmcnt(3)
	s_branch .Lfox_od_st

.Lfox_od_st:
	ds_write_b128 v129, v[6:9]
	ds_write_b128 v131, v[2:5] offset:18432
	s_and_saveexec_b64 s[0:1], s[38:39]
	s_cbranch_execz .LBB0_170
	ds_write_b32 v132, v141 offset:43008
	s_branch .LBB0_170
